# D-attention: next-tile staging (pack, ds_write, global loads) moved into the shadow of the last 8 PV MFMAs so K fragment reads start right after the barrier
# speedup vs baseline: 1.0052x; 1.0052x over previous
; #define LAS __attribute__((address_space(3)))
; DI unsigned pk2(float lo, float hi) { f32x2 v = {lo, hi}; bf16x2_t b = __builtin_convertvector(v, bf16x2_t); return __builtin_bit_cast(unsigned, b); }
; DI void attn_unit_d32(const Ctx& C, const bf16_t* __restrict__ Z, bf16_t* __restrict__ Y, int b, int qsel, int hsel, bool ctxq, float lam, float post_scale, const float* subln, const float mref) {
;     ...
;     for (int t = 0; t < nt; ++t) {
;         if (t + 1 < nt) {
;             if ((t + 1) & 1) { WRITE(1, kB, vB); if (t + 3 < nt) ISSUE(t + 3, kB, vB); }
;             else { WRITE(0, kA, vA); if (t + 3 < nt) ISSUE(t + 3, kA, vA); }
;         }
;         const LAS bf16_t* Ks = lds16 + ((t & 1) * AT_BUF) / 2 + 64 * sm; const LAS bf16_t* Vt = lds16 + ((t & 1) * AT_BUF + AT_VT) / 2;
;         f32x16 st[2];
; #pragma unroll
;         for (int kb = 0; kb < 2; ++kb) {
; #pragma unroll
;             for (int r = 0; r < 16; ++r) st[kb][r] = negm;
; #pragma unroll
;             for (int ks = 0; ks < 4; ++ks) { const bf16x8 a = *(const LAS bf16x8*)(Ks + (32 * kb + l31) * KST + 16 * ks + 8 * hh);
;                 st[kb] = __builtin_amdgcn_mfma_f32_32x32x16_bf16(a, qf[ks], st[kb], 0, 0, 0); } }
;         bf16x8 pf[2][2]; float ps = 0.f;
; #pragma unroll
;         for (int kb = 0; kb < 2; ++kb) {
; #pragma unroll
;             for (int r = 0; r < 16; ++r) { const float p = fast_exp2(st[kb][r]); st[kb][r] = p; ps += p; }
; #pragma unroll
;             for (int s = 0; s < 2; ++s) { u32x4 pw; pw.x = pk2(st[kb][8 * s], st[kb][8 * s + 1]); pw.y = pk2(st[kb][8 * s + 2], st[kb][8 * s + 3]); pw.z = pk2(st[kb][8 * s + 4], st[kb][8 * s + 5]); pw.w = pk2(st[kb][8 * s + 6], st[kb][8 * s + 7]);
;                 pf[kb][s] = __builtin_bit_cast(bf16x8, pw); } }
;         lsum += ps;
; #pragma unroll
;         for (int d = 0; d < 4; ++d)
; #pragma unroll
;             for (int kb = 0; kb < 2; ++kb)
; #pragma unroll
;                 for (int s = 0; s < 2; ++s) { const LAS bf16_t* vp = Vt + (32 * d + l31) * VST + 32 * kb + 16 * s + 4 * hh;
;                     const u32x2 lo = *(const LAS u32x2*)vp, hi = *(const LAS u32x2*)(vp + 8);
;                     u32x4 av; av.x = lo.x; av.y = lo.y; av.z = hi.x; av.w = hi.y;
;                     o[d] = __builtin_amdgcn_mfma_f32_32x32x16_bf16(__builtin_bit_cast(bf16x8, av), pf[kb][s], o[d], 0, 0, 0); }
.LBB0_399:
.LBB0_407:
	s_add_i32 s0, s23, 1
	s_bitcmp1_b32 s23, 0
	s_cselect_b32 s1, 0x9000, 0
	s_lshl_b32 s24, s18, 1
	s_add_i32 s24, s1, s24
	v_add3_u32 v194, s24, v183, v184
	ds_read_b128 v[84:87], v194
	ds_read_b128 v[88:91], v194 offset:32
	ds_read_b128 v[92:95], v194 offset:64
	ds_read_b128 v[96:99], v194 offset:96
	ds_read_b128 v[214:217], v194 offset:8704
	ds_read_b128 v[218:221], v194 offset:8736
	ds_read_b128 v[222:225], v194 offset:8768
	ds_read_b128 v[240:243], v194 offset:8800
	v_add3_u32 v195, s1, v183, v185
	ds_read_b128 v[244:247], v195 offset:17408
	ds_read_b128 v[210:213], v195 offset:17440
	s_waitcnt lgkmcnt(9)
	v_mfma_f32_32x32x16_bf16 v[100:115], v[84:87], v[116:119], v[4:19]
	s_waitcnt lgkmcnt(8)
	v_mfma_f32_32x32x16_bf16 v[100:115], v[88:91], v[120:123], v[100:115]
	s_waitcnt lgkmcnt(7)
	v_mfma_f32_32x32x16_bf16 v[100:115], v[92:95], v[124:127], v[100:115]
	s_waitcnt lgkmcnt(6)
	v_mfma_f32_32x32x16_bf16 v[100:115], v[96:99], v[128:131], v[100:115]
	s_waitcnt lgkmcnt(5)
	v_mfma_f32_32x32x16_bf16 v[84:99], v[214:217], v[116:119], v[4:19]
	ds_read_b128 v[214:217], v195 offset:22016
	s_waitcnt lgkmcnt(5)
	v_mfma_f32_32x32x16_bf16 v[84:99], v[218:221], v[120:123], v[84:99]
	ds_read_b128 v[218:221], v195 offset:22048
	s_waitcnt lgkmcnt(5)
	v_mfma_f32_32x32x16_bf16 v[84:99], v[222:225], v[124:127], v[84:99]
	ds_read_b128 v[222:225], v195 offset:26624
	s_waitcnt lgkmcnt(5)
	v_mfma_f32_32x32x16_bf16 v[84:99], v[240:243], v[128:131], v[84:99]
	ds_read_b128 v[240:243], v195 offset:26656
	v_exp_f32_e32 v100, v100
	v_exp_f32_e32 v101, v101
	v_exp_f32_e32 v102, v102
	v_add_f32_e32 v209, v101, v100
	v_exp_f32_e32 v103, v103
	v_add_f32_e32 v209, v102, v209
	v_exp_f32_e32 v104, v104
	v_add_f32_e32 v209, v103, v209
	v_exp_f32_e32 v105, v105
	v_add_f32_e32 v209, v104, v209
	v_exp_f32_e32 v106, v106
	v_add_f32_e32 v209, v105, v209
	v_exp_f32_e32 v107, v107
	v_add_f32_e32 v209, v106, v209
	v_exp_f32_e32 v108, v108
	v_add_f32_e32 v209, v107, v209
	v_exp_f32_e32 v109, v109
	v_add_f32_e32 v209, v108, v209
	v_exp_f32_e32 v110, v110
	v_add_f32_e32 v209, v109, v209
	v_exp_f32_e32 v111, v111
	v_add_f32_e32 v209, v110, v209
	v_exp_f32_e32 v112, v112
	v_add_f32_e32 v209, v111, v209
	v_exp_f32_e32 v113, v113
	v_add_f32_e32 v209, v112, v209
	v_exp_f32_e32 v114, v114
	v_add_f32_e32 v209, v113, v209
	v_exp_f32_e32 v115, v115
	v_add_f32_e32 v209, v114, v209
	v_cvt_pk_bf16_f32 v100, v100, v101
	v_add_f32_e32 v209, v115, v209
	v_cvt_pk_bf16_f32 v101, v102, v103
	v_cvt_pk_bf16_f32 v102, v104, v105
	v_cvt_pk_bf16_f32 v103, v106, v107
	v_cvt_pk_bf16_f32 v104, v108, v109
	v_cvt_pk_bf16_f32 v105, v110, v111
	v_cvt_pk_bf16_f32 v106, v112, v113
	v_cvt_pk_bf16_f32 v107, v114, v115
	ds_read_b128 v[108:111], v195 offset:31232
	ds_read_b128 v[112:115], v195 offset:31264
	s_waitcnt lgkmcnt(7)
	v_mfma_f32_32x32x16_bf16 v[68:83], v[244:247], v[100:103], v[68:83]
	ds_read_b128 v[244:247], v195 offset:17472
	v_exp_f32_e32 v84, v84
	v_exp_f32_e32 v85, v85
	v_add_f32_e32 v209, v84, v209
	v_exp_f32_e32 v86, v86
	v_add_f32_e32 v209, v85, v209
	s_waitcnt lgkmcnt(7)
	v_mfma_f32_32x32x16_bf16 v[68:83], v[210:213], v[104:107], v[68:83]
	ds_read_b128 v[210:213], v195 offset:17504
	v_exp_f32_e32 v87, v87
	v_add_f32_e32 v209, v86, v209
	v_exp_f32_e32 v88, v88
	v_add_f32_e32 v209, v87, v209
	v_exp_f32_e32 v89, v89
	s_waitcnt lgkmcnt(7)
	v_mfma_f32_32x32x16_bf16 v[52:67], v[214:217], v[100:103], v[52:67]
	ds_read_b128 v[214:217], v195 offset:22080
	v_add_f32_e32 v209, v88, v209
	v_exp_f32_e32 v90, v90
	v_add_f32_e32 v209, v89, v209
	v_exp_f32_e32 v91, v91
	v_add_f32_e32 v209, v90, v209
	s_waitcnt lgkmcnt(7)
	v_mfma_f32_32x32x16_bf16 v[52:67], v[218:221], v[104:107], v[52:67]
	ds_read_b128 v[218:221], v195 offset:22112
	v_exp_f32_e32 v92, v92
	v_add_f32_e32 v209, v91, v209
	v_exp_f32_e32 v93, v93
	v_add_f32_e32 v209, v92, v209
	v_exp_f32_e32 v94, v94
	s_waitcnt lgkmcnt(7)
	v_mfma_f32_32x32x16_bf16 v[36:51], v[222:225], v[100:103], v[36:51]
	ds_read_b128 v[222:225], v195 offset:26688
	v_add_f32_e32 v209, v93, v209
	v_exp_f32_e32 v95, v95
	v_add_f32_e32 v209, v94, v209
	v_exp_f32_e32 v96, v96
	v_add_f32_e32 v209, v95, v209
	s_waitcnt lgkmcnt(7)
	v_mfma_f32_32x32x16_bf16 v[36:51], v[240:243], v[104:107], v[36:51]
	ds_read_b128 v[240:243], v195 offset:26720
	v_exp_f32_e32 v97, v97
	v_add_f32_e32 v209, v96, v209
	v_exp_f32_e32 v98, v98
	v_add_f32_e32 v209, v97, v209
	v_exp_f32_e32 v99, v99
	s_waitcnt lgkmcnt(7)
	v_mfma_f32_32x32x16_bf16 v[20:35], v[108:111], v[100:103], v[20:35]
	ds_read_b128 v[108:111], v195 offset:31296
	v_add_f32_e32 v209, v98, v209
	v_cvt_pk_bf16_f32 v84, v84, v85
	v_add_f32_e32 v209, v99, v209
	v_cvt_pk_bf16_f32 v85, v86, v87
	v_cvt_pk_bf16_f32 v86, v88, v89
	s_waitcnt lgkmcnt(7)
	v_mfma_f32_32x32x16_bf16 v[20:35], v[112:115], v[104:107], v[20:35]
	ds_read_b128 v[112:115], v195 offset:31328
	v_cvt_pk_bf16_f32 v87, v90, v91
	v_cvt_pk_bf16_f32 v88, v92, v93
	v_cvt_pk_bf16_f32 v89, v94, v95
	v_cvt_pk_bf16_f32 v90, v96, v97
	v_cvt_pk_bf16_f32 v91, v98, v99
	s_cmp_gt_u32 s23, 34
	s_cbranch_scc1 .Ldt_plain
	s_bitcmp1_b32 s23, 0
	s_cbranch_scc0 .Ldt_even
; #define LAS __attribute__((address_space(3)))
; DI unsigned pk2(float lo, float hi) { f32x2 v = {lo, hi}; bf16x2_t b = __builtin_convertvector(v, bf16x2_t); return __builtin_bit_cast(unsigned, b); }
; DI void attn_unit_d32(const Ctx& C, const bf16_t* __restrict__ Z, bf16_t* __restrict__ Y, int b, int qsel, int hsel, bool ctxq, float lam, float post_scale, const float* subln, const float mref) {
;     ...
;         if (t + 1 < nt) {
;             if ((t + 1) & 1) { WRITE(1, kB, vB); if (t + 3 < nt) ISSUE(t + 3, kB, vB); }
;             else { WRITE(0, kA, vA); if (t + 3 < nt) ISSUE(t + 3, kA, vA); }
;         }
;         const LAS bf16_t* Ks = lds16 + ((t & 1) * AT_BUF) / 2 + 64 * sm; const LAS bf16_t* Vt = lds16 + ((t & 1) * AT_BUF + AT_VT) / 2;
;         f32x16 st[2];
; #pragma unroll
;         for (int kb = 0; kb < 2; ++kb) {
; #pragma unroll
;             for (int r = 0; r < 16; ++r) st[kb][r] = negm;
; #pragma unroll
;             for (int ks = 0; ks < 4; ++ks) { const bf16x8 a = *(const LAS bf16x8*)(Ks + (32 * kb + l31) * KST + 16 * ks + 8 * hh);
;                 st[kb] = __builtin_amdgcn_mfma_f32_32x32x16_bf16(a, qf[ks], st[kb], 0, 0, 0); } }
;         bf16x8 pf[2][2]; float ps = 0.f;
; #pragma unroll
;         for (int kb = 0; kb < 2; ++kb) {
; #pragma unroll
;             for (int r = 0; r < 16; ++r) { const float p = fast_exp2(st[kb][r]); st[kb][r] = p; ps += p; }
; #pragma unroll
;             for (int s = 0; s < 2; ++s) { u32x4 pw; pw.x = pk2(st[kb][8 * s], st[kb][8 * s + 1]); pw.y = pk2(st[kb][8 * s + 2], st[kb][8 * s + 3]); pw.z = pk2(st[kb][8 * s + 4], st[kb][8 * s + 5]); pw.w = pk2(st[kb][8 * s + 6], st[kb][8 * s + 7]);
;                 pf[kb][s] = __builtin_bit_cast(bf16x8, pw); } }
;         lsum += ps;
; #pragma unroll
;         for (int d = 0; d < 4; ++d)
; #pragma unroll
;             for (int kb = 0; kb < 2; ++kb)
; #pragma unroll
;                 for (int s = 0; s < 2; ++s) { const LAS bf16_t* vp = Vt + (32 * d + l31) * VST + 32 * kb + 16 * s + 4 * hh;
;                     const u32x2 lo = *(const LAS u32x2*)vp, hi = *(const LAS u32x2*)(vp + 8);
;                     u32x4 av; av.x = lo.x; av.y = lo.y; av.z = hi.x; av.w = hi.y;
;                     o[d] = __builtin_amdgcn_mfma_f32_32x32x16_bf16(__builtin_bit_cast(bf16x8, av), pf[kb][s], o[d], 0, 0, 0); }
;         __syncthreads();
.Ldt_odd:
	s_waitcnt lgkmcnt(7)
	v_mfma_f32_32x32x16_bf16 v[68:83], v[244:247], v[84:87], v[68:83]
	s_waitcnt vmcnt(4)
	v_lshlrev_b32_e32 v92, 16, v144
	v_lshrrev_b32_e32 v93, 16, v140
	v_and_or_b32 v92, v140, s40, v92
	v_and_or_b32 v93, v144, s39, v93
	s_waitcnt lgkmcnt(6)
	v_mfma_f32_32x32x16_bf16 v[68:83], v[210:213], v[88:91], v[68:83]
	ds_write_b128 v181, v[136:139]
	v_lshlrev_b32_e32 v94, 16, v145
	v_lshrrev_b32_e32 v95, 16, v141
	v_and_or_b32 v94, v141, s40, v94
	v_and_or_b32 v95, v145, s39, v95
	s_waitcnt lgkmcnt(6)
	v_mfma_f32_32x32x16_bf16 v[52:67], v[214:217], v[84:87], v[52:67]
	ds_write_b128 v181, v[132:135] offset:128
	v_lshlrev_b32_e32 v96, 16, v146
	v_lshrrev_b32_e32 v97, 16, v142
	v_and_or_b32 v96, v142, s40, v96
	v_and_or_b32 v97, v146, s39, v97
	s_waitcnt lgkmcnt(6)
	v_mfma_f32_32x32x16_bf16 v[52:67], v[218:221], v[88:91], v[52:67]
	ds_write2_b32 v191, v92, v93 offset1:36
	v_lshlrev_b32_e32 v98, 16, v147
	v_lshrrev_b32_e32 v99, 16, v143
	v_and_or_b32 v98, v143, s40, v98
	v_and_or_b32 v99, v147, s39, v99
	s_waitcnt lgkmcnt(6)
	v_mfma_f32_32x32x16_bf16 v[36:51], v[222:225], v[84:87], v[36:51]
	ds_write2_b32 v191, v94, v95 offset0:72 offset1:108
	s_mul_i32 s24, s22, 0x2200
	s_mul_hi_i32 s25, s22, 0x2200
	s_waitcnt lgkmcnt(6)
	v_mfma_f32_32x32x16_bf16 v[36:51], v[240:243], v[88:91], v[36:51]
	ds_write2_b32 v191, v96, v97 offset0:144 offset1:180
	ds_write2_b32 v191, v98, v99 offset0:216 offset1:252
	s_add_u32 s24, s8, s24
	s_addc_u32 s25, s9, s25
	s_waitcnt lgkmcnt(7)
	v_mfma_f32_32x32x16_bf16 v[20:35], v[108:111], v[84:87], v[20:35]
	s_cmp_gt_u32 s23, 32
	s_cbranch_scc1 .Ldt_odd_nl
	v_lshl_add_u64 v[96:97], v[0:1], 1, s[24:25]
	v_lshl_add_u64 v[92:93], v[174:175], 1, s[24:25]
	v_add_co_u32_e32 v94, vcc, 0x2000, v92
	global_load_dwordx4 v[136:139], v[96:97], off
	global_load_dwordx4 v[132:135], v[96:97], off offset:128
	v_addc_co_u32_e32 v95, vcc, 0, v93, vcc
	global_load_dwordx4 v[140:143], v[92:93], off
	global_load_dwordx4 v[144:147], v[94:95], off offset:512
.Ldt_odd_nl:
	s_waitcnt lgkmcnt(0)
	s_barrier
	v_mfma_f32_32x32x16_bf16 v[20:35], v[112:115], v[88:91], v[20:35]
	v_add_f32_e32 v193, v193, v209
	s_add_i32 s22, s22, 64
	s_branch .LBB0_398
.Ldt_even:
	s_waitcnt lgkmcnt(7)
	v_mfma_f32_32x32x16_bf16 v[68:83], v[244:247], v[84:87], v[68:83]
	s_cmp_gt_u32 s23, 32
	s_cbranch_scc1 .Ldt_even_w0
	s_waitcnt vmcnt(4)
	s_branch .Ldt_even_w1

; #define LAS __attribute__((address_space(3)))
; DI unsigned pk2(float lo, float hi) { f32x2 v = {lo, hi}; bf16x2_t b = __builtin_convertvector(v, bf16x2_t); return __builtin_bit_cast(unsigned, b); }
; DI void attn_unit_d32(const Ctx& C, const bf16_t* __restrict__ Z, bf16_t* __restrict__ Y, int b, int qsel, int hsel, bool ctxq, float lam, float post_scale, const float* subln, const float mref) {
;     ...
;         if (t + 1 < nt) {
;             if ((t + 1) & 1) { WRITE(1, kB, vB); if (t + 3 < nt) ISSUE(t + 3, kB, vB); }
;             else { WRITE(0, kA, vA); if (t + 3 < nt) ISSUE(t + 3, kA, vA); }
;         }
;         const LAS bf16_t* Ks = lds16 + ((t & 1) * AT_BUF) / 2 + 64 * sm; const LAS bf16_t* Vt = lds16 + ((t & 1) * AT_BUF + AT_VT) / 2;
;         f32x16 st[2];
; #pragma unroll
;         for (int kb = 0; kb < 2; ++kb) {
; #pragma unroll
;             for (int r = 0; r < 16; ++r) st[kb][r] = negm;
; #pragma unroll
;             for (int ks = 0; ks < 4; ++ks) { const bf16x8 a = *(const LAS bf16x8*)(Ks + (32 * kb + l31) * KST + 16 * ks + 8 * hh);
;                 st[kb] = __builtin_amdgcn_mfma_f32_32x32x16_bf16(a, qf[ks], st[kb], 0, 0, 0); } }
;         bf16x8 pf[2][2]; float ps = 0.f;
; #pragma unroll
;         for (int kb = 0; kb < 2; ++kb) {
; #pragma unroll
;             for (int r = 0; r < 16; ++r) { const float p = fast_exp2(st[kb][r]); st[kb][r] = p; ps += p; }
; #pragma unroll
;             for (int s = 0; s < 2; ++s) { u32x4 pw; pw.x = pk2(st[kb][8 * s], st[kb][8 * s + 1]); pw.y = pk2(st[kb][8 * s + 2], st[kb][8 * s + 3]); pw.z = pk2(st[kb][8 * s + 4], st[kb][8 * s + 5]); pw.w = pk2(st[kb][8 * s + 6], st[kb][8 * s + 7]);
;                 pf[kb][s] = __builtin_bit_cast(bf16x8, pw); } }
;         lsum += ps;
; #pragma unroll
;         for (int d = 0; d < 4; ++d)
; #pragma unroll
;             for (int kb = 0; kb < 2; ++kb)
; #pragma unroll
;                 for (int s = 0; s < 2; ++s) { const LAS bf16_t* vp = Vt + (32 * d + l31) * VST + 32 * kb + 16 * s + 4 * hh;
;                     const u32x2 lo = *(const LAS u32x2*)vp, hi = *(const LAS u32x2*)(vp + 8);
;                     u32x4 av; av.x = lo.x; av.y = lo.y; av.z = hi.x; av.w = hi.y;
;                     o[d] = __builtin_amdgcn_mfma_f32_32x32x16_bf16(__builtin_bit_cast(bf16x8, av), pf[kb][s], o[d], 0, 0, 0); }
;         __syncthreads();
.Ldt_even_w1:
	v_lshlrev_b32_e32 v92, 16, v160
	v_lshrrev_b32_e32 v93, 16, v156
	v_and_or_b32 v92, v156, s40, v92
	v_and_or_b32 v93, v160, s39, v93
	s_waitcnt lgkmcnt(6)
	v_mfma_f32_32x32x16_bf16 v[68:83], v[210:213], v[88:91], v[68:83]
	ds_write_b128 v181, v[148:151] offset:36864
	v_lshlrev_b32_e32 v94, 16, v161
	v_lshrrev_b32_e32 v95, 16, v157
	v_and_or_b32 v94, v157, s40, v94
	v_and_or_b32 v95, v161, s39, v95
	s_waitcnt lgkmcnt(6)
	v_mfma_f32_32x32x16_bf16 v[52:67], v[214:217], v[84:87], v[52:67]
	ds_write_b128 v181, v[152:155] offset:36992
	v_lshlrev_b32_e32 v96, 16, v162
	v_lshrrev_b32_e32 v97, 16, v158
	v_and_or_b32 v96, v158, s40, v96
	v_and_or_b32 v97, v162, s39, v97
	s_waitcnt lgkmcnt(6)
	v_mfma_f32_32x32x16_bf16 v[52:67], v[218:221], v[88:91], v[52:67]
	ds_write2_b32 v192, v92, v93 offset1:36
	v_lshlrev_b32_e32 v98, 16, v163
	v_lshrrev_b32_e32 v99, 16, v159
	v_and_or_b32 v98, v159, s40, v98
	v_and_or_b32 v99, v163, s39, v99
	s_waitcnt lgkmcnt(6)
	v_mfma_f32_32x32x16_bf16 v[36:51], v[222:225], v[84:87], v[36:51]
	ds_write2_b32 v192, v94, v95 offset0:72 offset1:108
	s_mul_i32 s24, s22, 0x2200
	s_mul_hi_i32 s25, s22, 0x2200
	s_waitcnt lgkmcnt(6)
	v_mfma_f32_32x32x16_bf16 v[36:51], v[240:243], v[88:91], v[36:51]
	ds_write2_b32 v192, v96, v97 offset0:144 offset1:180
	ds_write2_b32 v192, v98, v99 offset0:216 offset1:252
	s_add_u32 s24, s8, s24
	s_addc_u32 s25, s9, s25
	s_waitcnt lgkmcnt(7)
	v_mfma_f32_32x32x16_bf16 v[20:35], v[108:111], v[84:87], v[20:35]
	s_cmp_gt_u32 s23, 32
	s_cbranch_scc1 .Ldt_even_nl
	v_lshl_add_u64 v[96:97], v[0:1], 1, s[24:25]
	v_lshl_add_u64 v[92:93], v[174:175], 1, s[24:25]
	v_add_co_u32_e32 v94, vcc, 0x2000, v92
	global_load_dwordx4 v[148:151], v[96:97], off
	global_load_dwordx4 v[152:155], v[96:97], off offset:128
	v_addc_co_u32_e32 v95, vcc, 0, v93, vcc
	global_load_dwordx4 v[156:159], v[92:93], off
	global_load_dwordx4 v[160:163], v[94:95], off offset:512

; #define LAS __attribute__((address_space(3)))
; DI float shx(float v, int m, int lane) { return __builtin_bit_cast(float, __builtin_amdgcn_ds_bpermute((lane ^ m) << 2, __builtin_bit_cast(int, v))); }
; DI void attn_unit_d32(const Ctx& C, const bf16_t* __restrict__ Z, bf16_t* __restrict__ Y, int b, int qsel, int hsel, bool ctxq, float lam, float post_scale, const float* subln, const float mref) {
;     ...
;         for (int d = 0; d < 4; ++d)
; #pragma unroll
;             for (int kb = 0; kb < 2; ++kb)
; #pragma unroll
;                 for (int s = 0; s < 2; ++s) { const LAS bf16_t* vp = Vt + (32 * d + l31) * VST + 32 * kb + 16 * s + 4 * hh;
;                     const u32x2 lo = *(const LAS u32x2*)vp, hi = *(const LAS u32x2*)(vp + 8);
;                     u32x4 av; av.x = lo.x; av.y = lo.y; av.z = hi.x; av.w = hi.y;
;                     o[d] = __builtin_amdgcn_mfma_f32_32x32x16_bf16(__builtin_bit_cast(bf16x8, av), pf[kb][s], o[d], 0, 0, 0); }
;         __syncthreads();
;     }
;     ...
;     float l = lsum; l += shx(l, 32, lane); const float linv = 1.f / l;
;     LAS float* X = (LAS float*)C.lds + (32 * qg + l31) * 132;
;     if (sm == 1) {
; #pragma unroll
;         for (int d = 0; d < 4; ++d)
; #pragma unroll
;             for (int g = 0; g < 4; ++g) { const f32x4 v = {o[d][4 * g] * linv, o[d][4 * g + 1] * linv, o[d][4 * g + 2] * linv, o[d][4 * g + 3] * linv};
;                 *(LAS f32x4*)(X + 32 * d + 8 * g + 4 * hh) = v; }
;     }
.Ldt_plain:
	s_waitcnt lgkmcnt(7)
	v_mfma_f32_32x32x16_bf16 v[68:83], v[244:247], v[84:87], v[68:83]
	s_waitcnt lgkmcnt(6)
	v_mfma_f32_32x32x16_bf16 v[68:83], v[210:213], v[88:91], v[68:83]
	s_waitcnt lgkmcnt(5)
	v_mfma_f32_32x32x16_bf16 v[52:67], v[214:217], v[84:87], v[52:67]
	s_waitcnt lgkmcnt(4)
	v_mfma_f32_32x32x16_bf16 v[52:67], v[218:221], v[88:91], v[52:67]
	s_waitcnt lgkmcnt(3)
	v_mfma_f32_32x32x16_bf16 v[36:51], v[222:225], v[84:87], v[36:51]
	s_waitcnt lgkmcnt(2)
	v_mfma_f32_32x32x16_bf16 v[36:51], v[240:243], v[88:91], v[36:51]
	s_waitcnt lgkmcnt(1)
	v_mfma_f32_32x32x16_bf16 v[20:35], v[108:111], v[84:87], v[20:35]
	s_waitcnt lgkmcnt(0)
	s_barrier
	v_mfma_f32_32x32x16_bf16 v[20:35], v[112:115], v[88:91], v[20:35]
	v_add_f32_e32 v193, v193, v209
	s_add_i32 s22, s22, 64
	ds_bpermute_b32 v0, v186, v193
	s_waitcnt lgkmcnt(0)
	v_add_f32_e32 v0, v193, v0
	v_div_scale_f32 v84, s[0:1], v0, v0, 1.0
	v_rcp_f32_e32 v85, v84
	s_nop 0
	v_fma_f32 v86, -v84, v85, 1.0
	v_fmac_f32_e32 v85, v86, v85
	v_div_scale_f32 v86, vcc, 1.0, v0, 1.0
	v_mul_f32_e32 v87, v86, v85
	v_fma_f32 v88, -v84, v87, v86
	v_fmac_f32_e32 v87, v88, v85
	v_fma_f32 v84, -v84, v87, v86
	v_div_fmas_f32 v84, v84, v85, v87
	v_div_fixup_f32 v0, v84, v0, 1.0
	s_andn2_b64 vcc, exec, s[6:7]
	s_cbranch_vccnz .LBB0_410
	v_pk_mul_f32 v[84:85], v[68:69], v[0:1] op_sel_hi:[1,0]
	v_pk_mul_f32 v[86:87], v[70:71], v[0:1] op_sel_hi:[1,0]
	ds_write_b128 v190, v[84:87]
	v_pk_mul_f32 v[84:85], v[72:73], v[0:1] op_sel_hi:[1,0]
	v_pk_mul_f32 v[86:87], v[74:75], v[0:1] op_sel_hi:[1,0]
	ds_write_b128 v190, v[84:87] offset:32
	v_pk_mul_f32 v[84:85], v[76:77], v[0:1] op_sel_hi:[1,0]
	v_pk_mul_f32 v[86:87], v[78:79], v[0:1] op_sel_hi:[1,0]
	ds_write_b128 v190, v[84:87] offset:64
	v_pk_mul_f32 v[84:85], v[80:81], v[0:1] op_sel_hi:[1,0]
	v_pk_mul_f32 v[86:87], v[82:83], v[0:1] op_sel_hi:[1,0]
	ds_write_b128 v190, v[84:87] offset:96
	v_pk_mul_f32 v[84:85], v[52:53], v[0:1] op_sel_hi:[1,0]
	v_pk_mul_f32 v[86:87], v[54:55], v[0:1] op_sel_hi:[1,0]
	ds_write_b128 v190, v[84:87] offset:128
	v_pk_mul_f32 v[84:85], v[56:57], v[0:1] op_sel_hi:[1,0]
	v_pk_mul_f32 v[86:87], v[58:59], v[0:1] op_sel_hi:[1,0]
	ds_write_b128 v190, v[84:87] offset:160
	v_pk_mul_f32 v[84:85], v[60:61], v[0:1] op_sel_hi:[1,0]
	v_pk_mul_f32 v[86:87], v[62:63], v[0:1] op_sel_hi:[1,0]
	ds_write_b128 v190, v[84:87] offset:192
	v_pk_mul_f32 v[84:85], v[64:65], v[0:1] op_sel_hi:[1,0]
	v_pk_mul_f32 v[86:87], v[66:67], v[0:1] op_sel_hi:[1,0]
	ds_write_b128 v190, v[84:87] offset:224
	v_pk_mul_f32 v[84:85], v[36:37], v[0:1] op_sel_hi:[1,0]
	v_pk_mul_f32 v[86:87], v[38:39], v[0:1] op_sel_hi:[1,0]
	ds_write_b128 v190, v[84:87] offset:256
	v_pk_mul_f32 v[84:85], v[40:41], v[0:1] op_sel_hi:[1,0]
	v_pk_mul_f32 v[86:87], v[42:43], v[0:1] op_sel_hi:[1,0]
	ds_write_b128 v190, v[84:87] offset:288
	v_pk_mul_f32 v[84:85], v[44:45], v[0:1] op_sel_hi:[1,0]
	v_pk_mul_f32 v[86:87], v[46:47], v[0:1] op_sel_hi:[1,0]
	ds_write_b128 v190, v[84:87] offset:320
	v_pk_mul_f32 v[84:85], v[48:49], v[0:1] op_sel_hi:[1,0]
	v_pk_mul_f32 v[86:87], v[50:51], v[0:1] op_sel_hi:[1,0]
	ds_write_b128 v190, v[84:87] offset:352
	v_pk_mul_f32 v[84:85], v[20:21], v[0:1] op_sel_hi:[1,0]
	v_pk_mul_f32 v[86:87], v[22:23], v[0:1] op_sel_hi:[1,0]
	ds_write_b128 v190, v[84:87] offset:384
	v_pk_mul_f32 v[84:85], v[24:25], v[0:1] op_sel_hi:[1,0]
	v_pk_mul_f32 v[86:87], v[26:27], v[0:1] op_sel_hi:[1,0]
	ds_write_b128 v190, v[84:87] offset:416
	v_pk_mul_f32 v[84:85], v[28:29], v[0:1] op_sel_hi:[1,0]
	v_pk_mul_f32 v[86:87], v[30:31], v[0:1] op_sel_hi:[1,0]
	ds_write_b128 v190, v[84:87] offset:448
	v_pk_mul_f32 v[84:85], v[32:33], v[0:1] op_sel_hi:[1,0]
	v_pk_mul_f32 v[86:87], v[34:35], v[0:1] op_sel_hi:[1,0]
	ds_write_b128 v190, v[84:87] offset:480
